# P0 weight transposes hand-written: dwordx4 loads, pipelined items
# baseline (speedup 1.0000x reference)
.LBB0_5:
	s_or_b64 exec, exec, s[4:5]
	v_mov_b32_e32 v3, v228
	s_load_dwordx2 s[8:9], s[0:1], 0xc0
	s_load_dwordx16 s[36:51], s[0:1], 0x0
	v_readfirstlane_b32 s5, v3
	v_readlane_b32 s4, v254, 0
	s_ashr_i32 s6, s5, 6
	s_lshl_b32 s4, s4, 3
	v_and_b32_e32 v2, 63, v3
	v_writelane_b32 v254, s4, 5
	s_add_i32 s4, s6, s4
	s_waitcnt lgkmcnt(0)
	s_lshl_b32 s14, s8, 3
	s_cmpk_gt_i32 s4, 0x1cff
	v_lshlrev_b32_e32 v34, 3, v2
	v_writelane_b32 v254, s14, 6
	s_cbranch_scc1 .LBB0_24
	s_lshl_b32 s6, s6, 14
	v_lshrrev_b32_e32 v1, 3, v2
	v_and_b32_e32 v3, 7, v2
	v_mul_u32_u24_e32 v4, 0x84, v1
	v_lshlrev_b32_e32 v5, 4, v3
	v_add3_u32 v4, s6, v4, v5
	v_mul_u32_u24_e32 v5, 0x420, v3
	v_lshlrev_b32_e32 v6, 2, v1
	v_add3_u32 v5, s6, v5, v6
	v_lshlrev_b32_e32 v6, 4, v3
	v_mov_b32_e32 v7, 0
	v_lshlrev_b32_e32 v8, 5, v3
	v_mov_b32_e32 v9, 0
	s_mov_b32 s7, s4
	s_cmpk_lt_u32 s7, 0xb00
	s_cbranch_scc0 .Ltr_m1_i0
	s_mul_i32 s8, s7, 0x1746
	s_lshr_b32 s8, s8, 20
	s_mul_i32 s9, s8, 0xb0
	s_sub_u32 s9, s7, s9
	s_mov_b64 s[10:11], s[48:49]
	s_movk_i32 s12, 0x5800
	s_movk_i32 s13, 0x400
	s_add_u32 s16, s82, 0x80000
	s_addc_u32 s17, s83, 0
	s_mov_b64 s[18:19], s[72:73]
	s_branch .Ltr_go_i0
.Ltr_m1_i0:
	s_cmpk_lt_u32 s7, 0xd00
	s_cbranch_scc0 .Ltr_m2_i0
	s_sub_u32 s15, s7, 0xb00
	s_lshr_b32 s8, s15, 5
	s_and_b32 s9, s15, 31
	s_mov_b64 s[10:11], s[50:51]
	s_movk_i32 s12, 0x1000
	s_movk_i32 s13, 0x400
	s_add_u32 s16, s82, 0xb80000
	s_addc_u32 s17, s83, 0
	s_mov_b64 s[18:19], 0
	s_branch .Ltr_go_i0
.Ltr_m2_i0:
	s_cmpk_lt_u32 s7, 0x1500
	s_cbranch_scc0 .Ltr_m3_i0
	s_sub_u32 s15, s7, 0xd00
	s_lshr_b32 s8, s15, 7
	s_and_b32 s9, s15, 0x7f
	s_mov_b64 s[10:11], s[68:69]
	s_movk_i32 s12, 0x4000
	s_movk_i32 s13, 0x400
	s_add_u32 s16, s82, 0xd80000
	s_addc_u32 s17, s83, 0
	s_mov_b64 s[18:19], s[76:77]
	s_branch .Ltr_go_i0
.Ltr_m3_i0:
	s_sub_u32 s15, s7, 0x1500
	s_lshr_b32 s8, s15, 5
	s_and_b32 s9, s15, 31
	s_mov_b64 s[10:11], s[70:71]
	s_movk_i32 s12, 0x1000
	s_movk_i32 s13, 0x1000
	s_add_u32 s16, s82, 0x1580000
	s_addc_u32 s17, s83, 0
	s_mov_b64 s[18:19], 0
.Ltr_go_i0:
	s_lshl_b32 s15, s8, 6
	s_mul_i32 s20, s15, s12
	s_lshl_b32 s21, s9, 7
	s_add_u32 s20, s20, s21
	s_add_u32 s10, s10, s20
	s_addc_u32 s11, s11, 0
	s_lshl_b32 s20, s9, 6
	s_mul_i32 s20, s20, s13
	s_lshl_b32 s21, s15, 1
	s_add_u32 s20, s20, s21
	s_add_u32 s16, s16, s20
	s_addc_u32 s17, s17, 0
	s_cmp_lg_u64 s[18:19], 0
	s_cselect_b32 s28, 1, 0
	s_cselect_b64 s[22:23], s[18:19], s[10:11]
	s_lshl_b32 s21, s15, 2
	s_add_u32 s22, s22, s21
	s_addc_u32 s23, s23, 0
	v_mad_u64_u32 v[20:21], vcc, v1, s12, v[6:7]
	v_lshl_add_u64 v[20:21], s[10:11], 0, v[20:21]
	s_lshl_b32 s20, s12, 3
	s_mov_b32 s21, 0
	global_load_dwordx4 v[36:39], v[20:21], off
	v_lshl_add_u64 v[20:21], v[20:21], 0, s[20:21]
	global_load_dwordx4 v[40:43], v[20:21], off
	v_lshl_add_u64 v[20:21], v[20:21], 0, s[20:21]
	global_load_dwordx4 v[44:47], v[20:21], off
	v_lshl_add_u64 v[20:21], v[20:21], 0, s[20:21]
	global_load_dwordx4 v[48:51], v[20:21], off
	v_lshl_add_u64 v[20:21], v[20:21], 0, s[20:21]
	global_load_dwordx4 v[52:55], v[20:21], off
	v_lshl_add_u64 v[20:21], v[20:21], 0, s[20:21]
	global_load_dwordx4 v[56:59], v[20:21], off
	v_lshl_add_u64 v[20:21], v[20:21], 0, s[20:21]
	global_load_dwordx4 v[60:63], v[20:21], off
	v_lshl_add_u64 v[20:21], v[20:21], 0, s[20:21]
	global_load_dwordx4 v[64:67], v[20:21], off
	v_lshl_add_u64 v[22:23], s[22:23], 0, v[8:9]
	global_load_dwordx4 v[68:71], v[22:23], off
	global_load_dwordx4 v[72:75], v[22:23], off offset:16
	s_lshl_b32 s15, s13, 1
	v_mad_u64_u32 v[24:25], vcc, v1, s15, v[6:7]
	v_lshl_add_u64 v[24:25], s[16:17], 0, v[24:25]
	s_lshl_b32 s26, s13, 4
	s_mov_b32 s27, 0
.Ltr_loop:
	s_add_i32 s7, s7, s14
	s_cmpk_lt_u32 s7, 0x1d00
	s_cbranch_scc0 .Ltr_lastA
	s_cmpk_lt_u32 s7, 0xb00
	s_cbranch_scc0 .Ltr_m1_i1
	s_mul_i32 s8, s7, 0x1746
	s_lshr_b32 s8, s8, 20
	s_mul_i32 s9, s8, 0xb0
	s_sub_u32 s9, s7, s9
	s_mov_b64 s[10:11], s[48:49]
	s_movk_i32 s12, 0x5800
	s_movk_i32 s13, 0x400
	s_add_u32 s16, s82, 0x80000
	s_addc_u32 s17, s83, 0
	s_mov_b64 s[18:19], s[72:73]
	s_branch .Ltr_go_i1

.Ltr_go_i1:
	s_lshl_b32 s15, s8, 6
	s_mul_i32 s20, s15, s12
	s_lshl_b32 s21, s9, 7
	s_add_u32 s20, s20, s21
	s_add_u32 s10, s10, s20
	s_addc_u32 s11, s11, 0
	s_lshl_b32 s20, s9, 6
	s_mul_i32 s20, s20, s13
	s_lshl_b32 s21, s15, 1
	s_add_u32 s20, s20, s21
	s_add_u32 s16, s16, s20
	s_addc_u32 s17, s17, 0
	s_cmp_lg_u64 s[18:19], 0
	s_cselect_b32 s29, 1, 0
	s_cselect_b64 s[22:23], s[18:19], s[10:11]
	s_lshl_b32 s21, s15, 2
	s_add_u32 s22, s22, s21
	s_addc_u32 s23, s23, 0
	v_mad_u64_u32 v[20:21], vcc, v1, s12, v[6:7]
	v_lshl_add_u64 v[20:21], s[10:11], 0, v[20:21]
	s_lshl_b32 s20, s12, 3
	s_mov_b32 s21, 0
	global_load_dwordx4 v[108:111], v[20:21], off
	v_lshl_add_u64 v[20:21], v[20:21], 0, s[20:21]
	global_load_dwordx4 v[112:115], v[20:21], off
	v_lshl_add_u64 v[20:21], v[20:21], 0, s[20:21]
	global_load_dwordx4 v[116:119], v[20:21], off
	v_lshl_add_u64 v[20:21], v[20:21], 0, s[20:21]
	global_load_dwordx4 v[120:123], v[20:21], off
	v_lshl_add_u64 v[20:21], v[20:21], 0, s[20:21]
	global_load_dwordx4 v[124:127], v[20:21], off
	v_lshl_add_u64 v[20:21], v[20:21], 0, s[20:21]
	global_load_dwordx4 v[128:131], v[20:21], off
	v_lshl_add_u64 v[20:21], v[20:21], 0, s[20:21]
	global_load_dwordx4 v[132:135], v[20:21], off
	v_lshl_add_u64 v[20:21], v[20:21], 0, s[20:21]
	global_load_dwordx4 v[136:139], v[20:21], off
	v_lshl_add_u64 v[22:23], s[22:23], 0, v[8:9]
	global_load_dwordx4 v[140:143], v[22:23], off
	global_load_dwordx4 v[144:147], v[22:23], off offset:16
	s_lshl_b32 s15, s13, 1
	v_mad_u64_u32 v[30:31], vcc, v1, s15, v[6:7]
	v_lshl_add_u64 v[30:31], s[16:17], 0, v[30:31]
	s_lshl_b32 s30, s13, 4
	s_mov_b32 s31, 0
	s_waitcnt vmcnt(19)
	ds_write_b32 v4, v36
	ds_write_b32 v4, v37 offset:4
	ds_write_b32 v4, v38 offset:8
	ds_write_b32 v4, v39 offset:12
	s_waitcnt vmcnt(18)
	ds_write_b32 v4, v40 offset:1056
	ds_write_b32 v4, v41 offset:1060
	ds_write_b32 v4, v42 offset:1064
	ds_write_b32 v4, v43 offset:1068
	s_waitcnt vmcnt(17)
	ds_write_b32 v4, v44 offset:2112
	ds_write_b32 v4, v45 offset:2116
	ds_write_b32 v4, v46 offset:2120
	ds_write_b32 v4, v47 offset:2124
	s_waitcnt vmcnt(16)
	ds_write_b32 v4, v48 offset:3168
	ds_write_b32 v4, v49 offset:3172
	ds_write_b32 v4, v50 offset:3176
	ds_write_b32 v4, v51 offset:3180
	s_waitcnt vmcnt(15)
	ds_write_b32 v4, v52 offset:4224
	ds_write_b32 v4, v53 offset:4228
	ds_write_b32 v4, v54 offset:4232
	ds_write_b32 v4, v55 offset:4236
	s_waitcnt vmcnt(14)
	ds_write_b32 v4, v56 offset:5280
	ds_write_b32 v4, v57 offset:5284
	ds_write_b32 v4, v58 offset:5288
	ds_write_b32 v4, v59 offset:5292
	s_waitcnt vmcnt(13)
	ds_write_b32 v4, v60 offset:6336
	ds_write_b32 v4, v61 offset:6340
	ds_write_b32 v4, v62 offset:6344
	ds_write_b32 v4, v63 offset:6348
	s_waitcnt vmcnt(12)
	ds_write_b32 v4, v64 offset:7392
	ds_write_b32 v4, v65 offset:7396
	ds_write_b32 v4, v66 offset:7400
	ds_write_b32 v4, v67 offset:7404
	s_waitcnt vmcnt(10)
	s_cmp_lg_u32 s28, 0
	s_cbranch_scc1 .Ltr_havegk_pA
	v_mov_b32_e32 v68, 1.0
	v_mov_b32_e32 v69, 1.0
	v_mov_b32_e32 v70, 1.0
	v_mov_b32_e32 v71, 1.0
	v_mov_b32_e32 v72, 1.0
	v_mov_b32_e32 v73, 1.0
	v_mov_b32_e32 v74, 1.0
	v_mov_b32_e32 v75, 1.0
.Ltr_havegk_pA:
	ds_read2_b32 v[76:77], v5 offset1:33
	ds_read2_b32 v[78:79], v5 offset0:66 offset1:99
	ds_read2_b32 v[80:81], v5 offset0:132 offset1:165
	ds_read2_b32 v[82:83], v5 offset0:198 offset1:231
	ds_read2_b32 v[84:85], v5 offset0:8 offset1:41
	ds_read2_b32 v[86:87], v5 offset0:74 offset1:107
	ds_read2_b32 v[88:89], v5 offset0:140 offset1:173
	ds_read2_b32 v[90:91], v5 offset0:206 offset1:239
	ds_read2_b32 v[92:93], v5 offset0:16 offset1:49
	ds_read2_b32 v[94:95], v5 offset0:82 offset1:115
	ds_read2_b32 v[96:97], v5 offset0:148 offset1:181
	ds_read2_b32 v[98:99], v5 offset0:214 offset1:247
	ds_read2_b32 v[100:101], v5 offset0:24 offset1:57
	ds_read2_b32 v[102:103], v5 offset0:90 offset1:123
	ds_read2_b32 v[104:105], v5 offset0:156 offset1:189
	ds_read2_b32 v[106:107], v5 offset0:222 offset1:255
	s_waitcnt lgkmcnt(12)
	v_mul_f32_e32 v76, v76, v68
	v_mul_f32_e32 v77, v77, v69
	v_mul_f32_e32 v78, v78, v70
	v_mul_f32_e32 v79, v79, v71
	v_mul_f32_e32 v80, v80, v72
	v_mul_f32_e32 v81, v81, v73
	v_mul_f32_e32 v82, v82, v74
	v_mul_f32_e32 v83, v83, v75
	v_cvt_pk_bf16_f32 v76, v76, v77
	v_cvt_pk_bf16_f32 v77, v78, v79
	v_cvt_pk_bf16_f32 v78, v80, v81
	v_cvt_pk_bf16_f32 v79, v82, v83
	global_store_dwordx4 v[24:25], v[76:79], off
	v_lshl_add_u64 v[24:25], v[24:25], 0, s[26:27]
	s_waitcnt lgkmcnt(8)
	v_mul_f32_e32 v84, v84, v68
	v_mul_f32_e32 v85, v85, v69
	v_mul_f32_e32 v86, v86, v70
	v_mul_f32_e32 v87, v87, v71
	v_mul_f32_e32 v88, v88, v72
	v_mul_f32_e32 v89, v89, v73
	v_mul_f32_e32 v90, v90, v74
	v_mul_f32_e32 v91, v91, v75
	v_cvt_pk_bf16_f32 v84, v84, v85
	v_cvt_pk_bf16_f32 v85, v86, v87
	v_cvt_pk_bf16_f32 v86, v88, v89
	v_cvt_pk_bf16_f32 v87, v90, v91
	global_store_dwordx4 v[24:25], v[84:87], off
	v_lshl_add_u64 v[24:25], v[24:25], 0, s[26:27]
	s_waitcnt lgkmcnt(4)
	v_mul_f32_e32 v92, v92, v68
	v_mul_f32_e32 v93, v93, v69
	v_mul_f32_e32 v94, v94, v70
	v_mul_f32_e32 v95, v95, v71
	v_mul_f32_e32 v96, v96, v72
	v_mul_f32_e32 v97, v97, v73
	v_mul_f32_e32 v98, v98, v74
	v_mul_f32_e32 v99, v99, v75
	v_cvt_pk_bf16_f32 v92, v92, v93
	v_cvt_pk_bf16_f32 v93, v94, v95
	v_cvt_pk_bf16_f32 v94, v96, v97
	v_cvt_pk_bf16_f32 v95, v98, v99
	global_store_dwordx4 v[24:25], v[92:95], off
	v_lshl_add_u64 v[24:25], v[24:25], 0, s[26:27]
	s_waitcnt lgkmcnt(0)
	v_mul_f32_e32 v100, v100, v68
	v_mul_f32_e32 v101, v101, v69
	v_mul_f32_e32 v102, v102, v70
	v_mul_f32_e32 v103, v103, v71
	v_mul_f32_e32 v104, v104, v72
	v_mul_f32_e32 v105, v105, v73
	v_mul_f32_e32 v106, v106, v74
	v_mul_f32_e32 v107, v107, v75
	v_cvt_pk_bf16_f32 v100, v100, v101
	v_cvt_pk_bf16_f32 v101, v102, v103
	v_cvt_pk_bf16_f32 v102, v104, v105
	v_cvt_pk_bf16_f32 v103, v106, v107
	global_store_dwordx4 v[24:25], v[100:103], off
	s_add_i32 s7, s7, s14
	s_cmpk_lt_u32 s7, 0x1d00
	s_cbranch_scc0 .Ltr_lastB
	s_cmpk_lt_u32 s7, 0xb00
	s_cbranch_scc0 .Ltr_m1_i2
	s_mul_i32 s8, s7, 0x1746
	s_lshr_b32 s8, s8, 20
	s_mul_i32 s9, s8, 0xb0
	s_sub_u32 s9, s7, s9
	s_mov_b64 s[10:11], s[48:49]
	s_movk_i32 s12, 0x5800
	s_movk_i32 s13, 0x400
	s_add_u32 s16, s82, 0x80000
	s_addc_u32 s17, s83, 0
	s_mov_b64 s[18:19], s[72:73]
	s_branch .Ltr_go_i2

.Ltr_go_i2:
	s_lshl_b32 s15, s8, 6
	s_mul_i32 s20, s15, s12
	s_lshl_b32 s21, s9, 7
	s_add_u32 s20, s20, s21
	s_add_u32 s10, s10, s20
	s_addc_u32 s11, s11, 0
	s_lshl_b32 s20, s9, 6
	s_mul_i32 s20, s20, s13
	s_lshl_b32 s21, s15, 1
	s_add_u32 s20, s20, s21
	s_add_u32 s16, s16, s20
	s_addc_u32 s17, s17, 0
	s_cmp_lg_u64 s[18:19], 0
	s_cselect_b32 s28, 1, 0
	s_cselect_b64 s[22:23], s[18:19], s[10:11]
	s_lshl_b32 s21, s15, 2
	s_add_u32 s22, s22, s21
	s_addc_u32 s23, s23, 0
	v_mad_u64_u32 v[20:21], vcc, v1, s12, v[6:7]
	v_lshl_add_u64 v[20:21], s[10:11], 0, v[20:21]
	s_lshl_b32 s20, s12, 3
	s_mov_b32 s21, 0
	global_load_dwordx4 v[36:39], v[20:21], off
	v_lshl_add_u64 v[20:21], v[20:21], 0, s[20:21]
	global_load_dwordx4 v[40:43], v[20:21], off
	v_lshl_add_u64 v[20:21], v[20:21], 0, s[20:21]
	global_load_dwordx4 v[44:47], v[20:21], off
	v_lshl_add_u64 v[20:21], v[20:21], 0, s[20:21]
	global_load_dwordx4 v[48:51], v[20:21], off
	v_lshl_add_u64 v[20:21], v[20:21], 0, s[20:21]
	global_load_dwordx4 v[52:55], v[20:21], off
	v_lshl_add_u64 v[20:21], v[20:21], 0, s[20:21]
	global_load_dwordx4 v[56:59], v[20:21], off
	v_lshl_add_u64 v[20:21], v[20:21], 0, s[20:21]
	global_load_dwordx4 v[60:63], v[20:21], off
	v_lshl_add_u64 v[20:21], v[20:21], 0, s[20:21]
	global_load_dwordx4 v[64:67], v[20:21], off
	v_lshl_add_u64 v[22:23], s[22:23], 0, v[8:9]
	global_load_dwordx4 v[68:71], v[22:23], off
	global_load_dwordx4 v[72:75], v[22:23], off offset:16
	s_lshl_b32 s15, s13, 1
	v_mad_u64_u32 v[24:25], vcc, v1, s15, v[6:7]
	v_lshl_add_u64 v[24:25], s[16:17], 0, v[24:25]
	s_lshl_b32 s26, s13, 4
	s_mov_b32 s27, 0
	s_waitcnt vmcnt(23)
	ds_write_b32 v4, v108
	ds_write_b32 v4, v109 offset:4
	ds_write_b32 v4, v110 offset:8
	ds_write_b32 v4, v111 offset:12
	s_waitcnt vmcnt(22)
	ds_write_b32 v4, v112 offset:1056
	ds_write_b32 v4, v113 offset:1060
	ds_write_b32 v4, v114 offset:1064
	ds_write_b32 v4, v115 offset:1068
	s_waitcnt vmcnt(21)
	ds_write_b32 v4, v116 offset:2112
	ds_write_b32 v4, v117 offset:2116
	ds_write_b32 v4, v118 offset:2120
	ds_write_b32 v4, v119 offset:2124
	s_waitcnt vmcnt(20)
	ds_write_b32 v4, v120 offset:3168
	ds_write_b32 v4, v121 offset:3172
	ds_write_b32 v4, v122 offset:3176
	ds_write_b32 v4, v123 offset:3180
	s_waitcnt vmcnt(19)
	ds_write_b32 v4, v124 offset:4224
	ds_write_b32 v4, v125 offset:4228
	ds_write_b32 v4, v126 offset:4232
	ds_write_b32 v4, v127 offset:4236
	s_waitcnt vmcnt(18)
	ds_write_b32 v4, v128 offset:5280
	ds_write_b32 v4, v129 offset:5284
	ds_write_b32 v4, v130 offset:5288
	ds_write_b32 v4, v131 offset:5292
	s_waitcnt vmcnt(17)
	ds_write_b32 v4, v132 offset:6336
	ds_write_b32 v4, v133 offset:6340
	ds_write_b32 v4, v134 offset:6344
	ds_write_b32 v4, v135 offset:6348
	s_waitcnt vmcnt(16)
	ds_write_b32 v4, v136 offset:7392
	ds_write_b32 v4, v137 offset:7396
	ds_write_b32 v4, v138 offset:7400
	ds_write_b32 v4, v139 offset:7404
	s_waitcnt vmcnt(14)
	s_cmp_lg_u32 s29, 0
	s_cbranch_scc1 .Ltr_havegk_pB
	v_mov_b32_e32 v140, 1.0
	v_mov_b32_e32 v141, 1.0
	v_mov_b32_e32 v142, 1.0
	v_mov_b32_e32 v143, 1.0
	v_mov_b32_e32 v144, 1.0
	v_mov_b32_e32 v145, 1.0
	v_mov_b32_e32 v146, 1.0
	v_mov_b32_e32 v147, 1.0
.Ltr_havegk_pB:
	ds_read2_b32 v[76:77], v5 offset1:33
	ds_read2_b32 v[78:79], v5 offset0:66 offset1:99
	ds_read2_b32 v[80:81], v5 offset0:132 offset1:165
	ds_read2_b32 v[82:83], v5 offset0:198 offset1:231
	ds_read2_b32 v[84:85], v5 offset0:8 offset1:41
	ds_read2_b32 v[86:87], v5 offset0:74 offset1:107
	ds_read2_b32 v[88:89], v5 offset0:140 offset1:173
	ds_read2_b32 v[90:91], v5 offset0:206 offset1:239
	ds_read2_b32 v[92:93], v5 offset0:16 offset1:49
	ds_read2_b32 v[94:95], v5 offset0:82 offset1:115
	ds_read2_b32 v[96:97], v5 offset0:148 offset1:181
	ds_read2_b32 v[98:99], v5 offset0:214 offset1:247
	ds_read2_b32 v[100:101], v5 offset0:24 offset1:57
	ds_read2_b32 v[102:103], v5 offset0:90 offset1:123
	ds_read2_b32 v[104:105], v5 offset0:156 offset1:189
	ds_read2_b32 v[106:107], v5 offset0:222 offset1:255
	s_waitcnt lgkmcnt(12)
	v_mul_f32_e32 v76, v76, v140
	v_mul_f32_e32 v77, v77, v141
	v_mul_f32_e32 v78, v78, v142
	v_mul_f32_e32 v79, v79, v143
	v_mul_f32_e32 v80, v80, v144
	v_mul_f32_e32 v81, v81, v145
	v_mul_f32_e32 v82, v82, v146
	v_mul_f32_e32 v83, v83, v147
	v_cvt_pk_bf16_f32 v76, v76, v77
	v_cvt_pk_bf16_f32 v77, v78, v79
	v_cvt_pk_bf16_f32 v78, v80, v81
	v_cvt_pk_bf16_f32 v79, v82, v83
	global_store_dwordx4 v[30:31], v[76:79], off
	v_lshl_add_u64 v[30:31], v[30:31], 0, s[30:31]
	s_waitcnt lgkmcnt(8)
	v_mul_f32_e32 v84, v84, v140
	v_mul_f32_e32 v85, v85, v141
	v_mul_f32_e32 v86, v86, v142
	v_mul_f32_e32 v87, v87, v143
	v_mul_f32_e32 v88, v88, v144
	v_mul_f32_e32 v89, v89, v145
	v_mul_f32_e32 v90, v90, v146
	v_mul_f32_e32 v91, v91, v147
	v_cvt_pk_bf16_f32 v84, v84, v85
	v_cvt_pk_bf16_f32 v85, v86, v87
	v_cvt_pk_bf16_f32 v86, v88, v89
	v_cvt_pk_bf16_f32 v87, v90, v91
	global_store_dwordx4 v[30:31], v[84:87], off
	v_lshl_add_u64 v[30:31], v[30:31], 0, s[30:31]
	s_waitcnt lgkmcnt(4)
	v_mul_f32_e32 v92, v92, v140
	v_mul_f32_e32 v93, v93, v141
	v_mul_f32_e32 v94, v94, v142
	v_mul_f32_e32 v95, v95, v143
	v_mul_f32_e32 v96, v96, v144
	v_mul_f32_e32 v97, v97, v145
	v_mul_f32_e32 v98, v98, v146
	v_mul_f32_e32 v99, v99, v147
	v_cvt_pk_bf16_f32 v92, v92, v93
	v_cvt_pk_bf16_f32 v93, v94, v95
	v_cvt_pk_bf16_f32 v94, v96, v97
	v_cvt_pk_bf16_f32 v95, v98, v99
	global_store_dwordx4 v[30:31], v[92:95], off
	v_lshl_add_u64 v[30:31], v[30:31], 0, s[30:31]
	s_waitcnt lgkmcnt(0)
	v_mul_f32_e32 v100, v100, v140
	v_mul_f32_e32 v101, v101, v141
	v_mul_f32_e32 v102, v102, v142
	v_mul_f32_e32 v103, v103, v143
	v_mul_f32_e32 v104, v104, v144
	v_mul_f32_e32 v105, v105, v145
	v_mul_f32_e32 v106, v106, v146
	v_mul_f32_e32 v107, v107, v147
	v_cvt_pk_bf16_f32 v100, v100, v101
	v_cvt_pk_bf16_f32 v101, v102, v103
	v_cvt_pk_bf16_f32 v102, v104, v105
	v_cvt_pk_bf16_f32 v103, v106, v107
	global_store_dwordx4 v[30:31], v[100:103], off
	s_branch .Ltr_loop
.Ltr_lastA:
	s_waitcnt vmcnt(9)
	ds_write_b32 v4, v36
	ds_write_b32 v4, v37 offset:4
	ds_write_b32 v4, v38 offset:8
	ds_write_b32 v4, v39 offset:12
	s_waitcnt vmcnt(8)
	ds_write_b32 v4, v40 offset:1056
	ds_write_b32 v4, v41 offset:1060
	ds_write_b32 v4, v42 offset:1064
	ds_write_b32 v4, v43 offset:1068
	s_waitcnt vmcnt(7)
	ds_write_b32 v4, v44 offset:2112
	ds_write_b32 v4, v45 offset:2116
	ds_write_b32 v4, v46 offset:2120
	ds_write_b32 v4, v47 offset:2124
	s_waitcnt vmcnt(6)
	ds_write_b32 v4, v48 offset:3168
	ds_write_b32 v4, v49 offset:3172
	ds_write_b32 v4, v50 offset:3176
	ds_write_b32 v4, v51 offset:3180
	s_waitcnt vmcnt(5)
	ds_write_b32 v4, v52 offset:4224
	ds_write_b32 v4, v53 offset:4228
	ds_write_b32 v4, v54 offset:4232
	ds_write_b32 v4, v55 offset:4236
	s_waitcnt vmcnt(4)
	ds_write_b32 v4, v56 offset:5280
	ds_write_b32 v4, v57 offset:5284
	ds_write_b32 v4, v58 offset:5288
	ds_write_b32 v4, v59 offset:5292
	s_waitcnt vmcnt(3)
	ds_write_b32 v4, v60 offset:6336
	ds_write_b32 v4, v61 offset:6340
	ds_write_b32 v4, v62 offset:6344
	ds_write_b32 v4, v63 offset:6348
	s_waitcnt vmcnt(2)
	ds_write_b32 v4, v64 offset:7392
	ds_write_b32 v4, v65 offset:7396
	ds_write_b32 v4, v66 offset:7400
	ds_write_b32 v4, v67 offset:7404
	s_waitcnt vmcnt(0)
	s_cmp_lg_u32 s28, 0
	s_cbranch_scc1 .Ltr_havegk_lA
	v_mov_b32_e32 v68, 1.0
	v_mov_b32_e32 v69, 1.0
	v_mov_b32_e32 v70, 1.0
	v_mov_b32_e32 v71, 1.0
	v_mov_b32_e32 v72, 1.0
	v_mov_b32_e32 v73, 1.0
	v_mov_b32_e32 v74, 1.0
	v_mov_b32_e32 v75, 1.0
.Ltr_havegk_lA:
	ds_read2_b32 v[76:77], v5 offset1:33
	ds_read2_b32 v[78:79], v5 offset0:66 offset1:99
	ds_read2_b32 v[80:81], v5 offset0:132 offset1:165
	ds_read2_b32 v[82:83], v5 offset0:198 offset1:231
	ds_read2_b32 v[84:85], v5 offset0:8 offset1:41
	ds_read2_b32 v[86:87], v5 offset0:74 offset1:107
	ds_read2_b32 v[88:89], v5 offset0:140 offset1:173
	ds_read2_b32 v[90:91], v5 offset0:206 offset1:239
	ds_read2_b32 v[92:93], v5 offset0:16 offset1:49
	ds_read2_b32 v[94:95], v5 offset0:82 offset1:115
	ds_read2_b32 v[96:97], v5 offset0:148 offset1:181
	ds_read2_b32 v[98:99], v5 offset0:214 offset1:247
	ds_read2_b32 v[100:101], v5 offset0:24 offset1:57
	ds_read2_b32 v[102:103], v5 offset0:90 offset1:123
	ds_read2_b32 v[104:105], v5 offset0:156 offset1:189
	ds_read2_b32 v[106:107], v5 offset0:222 offset1:255
	s_waitcnt lgkmcnt(12)
	v_mul_f32_e32 v76, v76, v68
	v_mul_f32_e32 v77, v77, v69
	v_mul_f32_e32 v78, v78, v70
	v_mul_f32_e32 v79, v79, v71
	v_mul_f32_e32 v80, v80, v72
	v_mul_f32_e32 v81, v81, v73
	v_mul_f32_e32 v82, v82, v74
	v_mul_f32_e32 v83, v83, v75
	v_cvt_pk_bf16_f32 v76, v76, v77
	v_cvt_pk_bf16_f32 v77, v78, v79
	v_cvt_pk_bf16_f32 v78, v80, v81
	v_cvt_pk_bf16_f32 v79, v82, v83
	global_store_dwordx4 v[24:25], v[76:79], off
	v_lshl_add_u64 v[24:25], v[24:25], 0, s[26:27]
	s_waitcnt lgkmcnt(8)
	v_mul_f32_e32 v84, v84, v68
	v_mul_f32_e32 v85, v85, v69
	v_mul_f32_e32 v86, v86, v70
	v_mul_f32_e32 v87, v87, v71
	v_mul_f32_e32 v88, v88, v72
	v_mul_f32_e32 v89, v89, v73
	v_mul_f32_e32 v90, v90, v74
	v_mul_f32_e32 v91, v91, v75
	v_cvt_pk_bf16_f32 v84, v84, v85
	v_cvt_pk_bf16_f32 v85, v86, v87
	v_cvt_pk_bf16_f32 v86, v88, v89
	v_cvt_pk_bf16_f32 v87, v90, v91
	global_store_dwordx4 v[24:25], v[84:87], off
	v_lshl_add_u64 v[24:25], v[24:25], 0, s[26:27]
	s_waitcnt lgkmcnt(4)
	v_mul_f32_e32 v92, v92, v68
	v_mul_f32_e32 v93, v93, v69
	v_mul_f32_e32 v94, v94, v70
	v_mul_f32_e32 v95, v95, v71
	v_mul_f32_e32 v96, v96, v72
	v_mul_f32_e32 v97, v97, v73
	v_mul_f32_e32 v98, v98, v74
	v_mul_f32_e32 v99, v99, v75
	v_cvt_pk_bf16_f32 v92, v92, v93
	v_cvt_pk_bf16_f32 v93, v94, v95
	v_cvt_pk_bf16_f32 v94, v96, v97
	v_cvt_pk_bf16_f32 v95, v98, v99
	global_store_dwordx4 v[24:25], v[92:95], off
	v_lshl_add_u64 v[24:25], v[24:25], 0, s[26:27]
	s_waitcnt lgkmcnt(0)
	v_mul_f32_e32 v100, v100, v68
	v_mul_f32_e32 v101, v101, v69
	v_mul_f32_e32 v102, v102, v70
	v_mul_f32_e32 v103, v103, v71
	v_mul_f32_e32 v104, v104, v72
	v_mul_f32_e32 v105, v105, v73
	v_mul_f32_e32 v106, v106, v74
	v_mul_f32_e32 v107, v107, v75
	v_cvt_pk_bf16_f32 v100, v100, v101
	v_cvt_pk_bf16_f32 v101, v102, v103
	v_cvt_pk_bf16_f32 v102, v104, v105
	v_cvt_pk_bf16_f32 v103, v106, v107
	global_store_dwordx4 v[24:25], v[100:103], off
	s_branch .Ltr_done
.Ltr_lastB:
	s_waitcnt vmcnt(13)
	ds_write_b32 v4, v108
	ds_write_b32 v4, v109 offset:4
	ds_write_b32 v4, v110 offset:8
	ds_write_b32 v4, v111 offset:12
	s_waitcnt vmcnt(12)
	ds_write_b32 v4, v112 offset:1056
	ds_write_b32 v4, v113 offset:1060
	ds_write_b32 v4, v114 offset:1064
	ds_write_b32 v4, v115 offset:1068
	s_waitcnt vmcnt(11)
	ds_write_b32 v4, v116 offset:2112
	ds_write_b32 v4, v117 offset:2116
	ds_write_b32 v4, v118 offset:2120
	ds_write_b32 v4, v119 offset:2124
	s_waitcnt vmcnt(10)
	ds_write_b32 v4, v120 offset:3168
	ds_write_b32 v4, v121 offset:3172
	ds_write_b32 v4, v122 offset:3176
	ds_write_b32 v4, v123 offset:3180
	s_waitcnt vmcnt(9)
	ds_write_b32 v4, v124 offset:4224
	ds_write_b32 v4, v125 offset:4228
	ds_write_b32 v4, v126 offset:4232
	ds_write_b32 v4, v127 offset:4236
	s_waitcnt vmcnt(8)
	ds_write_b32 v4, v128 offset:5280
	ds_write_b32 v4, v129 offset:5284
	ds_write_b32 v4, v130 offset:5288
	ds_write_b32 v4, v131 offset:5292
	s_waitcnt vmcnt(7)
	ds_write_b32 v4, v132 offset:6336
	ds_write_b32 v4, v133 offset:6340
	ds_write_b32 v4, v134 offset:6344
	ds_write_b32 v4, v135 offset:6348
	s_waitcnt vmcnt(6)
	ds_write_b32 v4, v136 offset:7392
	ds_write_b32 v4, v137 offset:7396
	ds_write_b32 v4, v138 offset:7400
	ds_write_b32 v4, v139 offset:7404
	s_waitcnt vmcnt(4)
	s_cmp_lg_u32 s29, 0
	s_cbranch_scc1 .Ltr_havegk_lB
	v_mov_b32_e32 v140, 1.0
	v_mov_b32_e32 v141, 1.0
	v_mov_b32_e32 v142, 1.0
	v_mov_b32_e32 v143, 1.0
	v_mov_b32_e32 v144, 1.0
	v_mov_b32_e32 v145, 1.0
	v_mov_b32_e32 v146, 1.0
	v_mov_b32_e32 v147, 1.0
.Ltr_havegk_lB:
	ds_read2_b32 v[76:77], v5 offset1:33
	ds_read2_b32 v[78:79], v5 offset0:66 offset1:99
	ds_read2_b32 v[80:81], v5 offset0:132 offset1:165
	ds_read2_b32 v[82:83], v5 offset0:198 offset1:231
	ds_read2_b32 v[84:85], v5 offset0:8 offset1:41
	ds_read2_b32 v[86:87], v5 offset0:74 offset1:107
	ds_read2_b32 v[88:89], v5 offset0:140 offset1:173
	ds_read2_b32 v[90:91], v5 offset0:206 offset1:239
	ds_read2_b32 v[92:93], v5 offset0:16 offset1:49
	ds_read2_b32 v[94:95], v5 offset0:82 offset1:115
	ds_read2_b32 v[96:97], v5 offset0:148 offset1:181
	ds_read2_b32 v[98:99], v5 offset0:214 offset1:247
	ds_read2_b32 v[100:101], v5 offset0:24 offset1:57
	ds_read2_b32 v[102:103], v5 offset0:90 offset1:123
	ds_read2_b32 v[104:105], v5 offset0:156 offset1:189
	ds_read2_b32 v[106:107], v5 offset0:222 offset1:255
	s_waitcnt lgkmcnt(12)
	v_mul_f32_e32 v76, v76, v140
	v_mul_f32_e32 v77, v77, v141
	v_mul_f32_e32 v78, v78, v142
	v_mul_f32_e32 v79, v79, v143
	v_mul_f32_e32 v80, v80, v144
	v_mul_f32_e32 v81, v81, v145
	v_mul_f32_e32 v82, v82, v146
	v_mul_f32_e32 v83, v83, v147
	v_cvt_pk_bf16_f32 v76, v76, v77
	v_cvt_pk_bf16_f32 v77, v78, v79
	v_cvt_pk_bf16_f32 v78, v80, v81
	v_cvt_pk_bf16_f32 v79, v82, v83
	global_store_dwordx4 v[30:31], v[76:79], off
	v_lshl_add_u64 v[30:31], v[30:31], 0, s[30:31]
	s_waitcnt lgkmcnt(8)
	v_mul_f32_e32 v84, v84, v140
	v_mul_f32_e32 v85, v85, v141
	v_mul_f32_e32 v86, v86, v142
	v_mul_f32_e32 v87, v87, v143
	v_mul_f32_e32 v88, v88, v144
	v_mul_f32_e32 v89, v89, v145
	v_mul_f32_e32 v90, v90, v146
	v_mul_f32_e32 v91, v91, v147
	v_cvt_pk_bf16_f32 v84, v84, v85
	v_cvt_pk_bf16_f32 v85, v86, v87
	v_cvt_pk_bf16_f32 v86, v88, v89
	v_cvt_pk_bf16_f32 v87, v90, v91
	global_store_dwordx4 v[30:31], v[84:87], off
	v_lshl_add_u64 v[30:31], v[30:31], 0, s[30:31]
	s_waitcnt lgkmcnt(4)
	v_mul_f32_e32 v92, v92, v140
	v_mul_f32_e32 v93, v93, v141
	v_mul_f32_e32 v94, v94, v142
	v_mul_f32_e32 v95, v95, v143
	v_mul_f32_e32 v96, v96, v144
	v_mul_f32_e32 v97, v97, v145
	v_mul_f32_e32 v98, v98, v146
	v_mul_f32_e32 v99, v99, v147
	v_cvt_pk_bf16_f32 v92, v92, v93
	v_cvt_pk_bf16_f32 v93, v94, v95
	v_cvt_pk_bf16_f32 v94, v96, v97
	v_cvt_pk_bf16_f32 v95, v98, v99
	global_store_dwordx4 v[30:31], v[92:95], off
	v_lshl_add_u64 v[30:31], v[30:31], 0, s[30:31]
	s_waitcnt lgkmcnt(0)
	v_mul_f32_e32 v100, v100, v140
	v_mul_f32_e32 v101, v101, v141
	v_mul_f32_e32 v102, v102, v142
	v_mul_f32_e32 v103, v103, v143
	v_mul_f32_e32 v104, v104, v144
	v_mul_f32_e32 v105, v105, v145
	v_mul_f32_e32 v106, v106, v146
	v_mul_f32_e32 v107, v107, v147
	v_cvt_pk_bf16_f32 v100, v100, v101
	v_cvt_pk_bf16_f32 v101, v102, v103
	v_cvt_pk_bf16_f32 v102, v104, v105
	v_cvt_pk_bf16_f32 v103, v106, v107
	global_store_dwordx4 v[30:31], v[100:103], off
.Ltr_done:
.LBB0_24:
	v_lshl_or_b32 v1, s4, 6, v2
	s_mov_b32 s6, 0xfe000
	v_cmp_gt_i32_e32 vcc, s6, v1
	s_and_saveexec_b64 s[8:9], vcc
	v_writelane_b32 v254, s36, 7
	s_load_dwordx2 s[52:53], s[0:1], 0xc0
	s_nop 0
	v_writelane_b32 v254, s37, 8
	v_writelane_b32 v254, s38, 9
	v_writelane_b32 v254, s39, 10
	v_writelane_b32 v254, s40, 11
	v_writelane_b32 v254, s41, 12
	v_writelane_b32 v254, s42, 13
	v_writelane_b32 v254, s43, 14
	v_writelane_b32 v254, s44, 15
	v_writelane_b32 v254, s45, 16
	v_writelane_b32 v254, s46, 17
	v_writelane_b32 v254, s47, 18
	v_writelane_b32 v254, s48, 19
	v_writelane_b32 v254, s49, 20
	v_writelane_b32 v254, s50, 21
	v_writelane_b32 v254, s51, 22
	s_nop 0
	v_readlane_b32 s50, v254, 0
	s_cbranch_execz .LBB0_32
	s_add_u32 s10, s80, 0x84c0000
	s_addc_u32 s11, s81, 0
	s_add_u32 s12, s80, 0x94c0000
	s_addc_u32 s13, s81, 0
	s_waitcnt lgkmcnt(0)
	s_lshl_b32 s16, s52, 9
	v_cvt_f32_u32_e32 v3, s16
	s_add_i32 s7, s50, s52
	s_lshl_b32 s7, s7, 9
	s_andn2_b32 s5, s5, 63
	v_rcp_iflag_f32_e32 v3, v3
	s_add_i32 s7, s7, s5
	v_or_b32_e32 v4, s7, v2
	v_cmp_gt_i32_e32 vcc, s6, v4
	v_mul_f32_e32 v3, 0x4f7ffffe, v3
	v_cvt_u32_f32_e32 v3, v3
	v_max_i32_e32 v5, 0xfe000, v4
	v_addc_co_u32_e64 v4, s[6:7], 0, v4, vcc
	s_sub_i32 s5, 0, s16
	v_sub_u32_e32 v4, v5, v4
	v_mul_lo_u32 v5, s5, v3
	v_mul_hi_u32 v5, v3, v5
	v_add_u32_e32 v3, v3, v5
	v_mul_hi_u32 v3, v4, v3
	v_mul_lo_u32 v5, v3, s16
	v_sub_u32_e32 v4, v4, v5
	v_add_u32_e32 v5, 1, v3
	v_cmp_le_u32_e64 s[6:7], s16, v4
	s_nop 1
	v_cndmask_b32_e64 v3, v3, v5, s[6:7]
	v_subrev_u32_e32 v5, s16, v4
	v_cndmask_b32_e64 v4, v4, v5, s[6:7]
	v_add_u32_e32 v5, 1, v3
	v_cmp_le_u32_e64 s[6:7], s16, v4
	s_nop 1
	v_cndmask_b32_e64 v3, v3, v5, s[6:7]
	v_addc_co_u32_e32 v3, vcc, 0, v3, vcc
	v_and_b32_e32 v4, 3, v3
	v_cmp_ne_u32_e32 vcc, 3, v4
	s_and_saveexec_b64 s[6:7], vcc
	s_cbranch_execz .LBB0_29
	s_load_dwordx16 s[56:71], s[0:1], 0x0
	v_add_u32_e32 v4, 1, v3
	v_and_b32_e32 v4, 3, v4
	s_mov_b64 s[14:15], 0
	s_mov_b32 s5, 0x81020409
	s_waitcnt lgkmcnt(0)
	s_mov_b64 s[36:37], s[56:57]
	s_movk_i32 s17, 0xe040
	s_mov_b64 s[40:41], s[60:61]
	s_mov_b64 s[42:43], s[62:63]
	s_mov_b64 s[38:39], s[58:59]
	s_mov_b64 s[44:45], s[64:65]
	s_mov_b64 s[46:47], s[66:67]
